# down-projection epilogue: the write-once final output stores carry the nt hint
# baseline (speedup 1.0000x reference)
; #define EN_LOAD(BUF, G) do { const size_t bi_ = (size_t)(row0b + ((G) >> 2) * HALF + ((G) & 3) * 16) * DM + col0b; \
;             _Pragma("unroll") for (int bj = 0; bj < 2; ++bj) _Pragma("unroll") for (int n = 0; n < 2; ++n) BUF[bj][n] = ldb(baseP, bi_ + bj * HALF + n * 16); } while (0)
;     __device__ __forceinline__ void operator()(const f32x4 (&acc)[2][2][4][2], const Unit& u, int wr, int wc, int fr, int fq) const {
;     ...
;         asm volatile("s_waitcnt lgkmcnt(0)" ::: "memory"); __builtin_amdgcn_s_barrier(); asm volatile("" ::: "memory");
;         int row0b = row0, col0b = col0; asm volatile("" : "+v"(row0b), "+v"(col0b));
;         f32x4 c1[2][2], c2[2][2];
; #pragma unroll
;         for (int bj = 0; bj < 2; ++bj)
; #pragma unroll
;             for (int n = 0; n < 2; ++n) { c1[bj][n] = *(const f32x4*)(g + col0b + bj * HALF + n * 16);
;                 if (MODE == 0) { const float* mr = mod + (size_t)((u.pm * BM) >> 11) * NMOD + col0b + bj * HALF + n * 16; c1[bj][n] = c1[bj][n] * (*(const f32x4*)(mr + 4096) + 1.f); c2[bj][n] = *(const f32x4*)(mr + 3072); } }
;     ...
;         f32x4 bA[2][2], bB[2][2];
;         EN_LOAD(bA, 0); EN_LOAD(bB, 1);
;         EN_DONE(bA, 0); EN_LOAD(bA, 2); EN_DONE(bB, 1); EN_LOAD(bB, 3);
;         EN_DONE(bA, 2); EN_LOAD(bA, 4); EN_DONE(bB, 3); EN_LOAD(bB, 5);
;         EN_DONE(bA, 4); EN_LOAD(bA, 6); EN_DONE(bB, 5); EN_LOAD(bB, 7);
;         EN_DONE(bA, 6); EN_DONE(bB, 7);
.LBB0_1643:
	s_or_b64 exec, exec, s[14:15]
	v_mov_b32_e32 v146, v176
	v_mov_b32_e32 v148, v174
	s_waitcnt lgkmcnt(0)
	s_barrier
	v_lshl_add_u32 v175, v183, 2, s84
	ds_read_b32 v192, v175 offset:4096
	ds_read_b32 v194, v175 offset:4160
	ds_read_b32 v196, v175 offset:4224
	ds_read_b32 v198, v175 offset:4288
	ds_read_b32 v200, v175 offset:4608
	ds_read_b32 v202, v175 offset:4672
	ds_read_b32 v204, v175 offset:4736
	ds_read_b32 v206, v175 offset:4800
	v_lshlrev_b64 v[178:179], 2, v[176:177]
	v_lshl_add_u64 v[146:147], s[20:21], 0, v[178:179]
	global_load_dwordx4 v[158:161], v[146:147], off
	global_load_dwordx4 v[154:157], v[146:147], off offset:64
	global_load_dwordx4 v[150:153], v[146:147], off offset:512
	s_nop 0
	global_load_dwordx4 v[146:149], v[146:147], off offset:576
	v_add_u32_e32 v182, s41, v183
	v_ashrrev_i32_e32 v183, 31, v182
	v_lshlrev_b64 v[180:181], 12, v[182:183]
	v_lshl_add_u64 v[180:181], s[18:19], 0, v[180:181]
	v_lshl_add_u64 v[180:181], v[180:181], 0, v[178:179]
	s_mov_b64 s[24:25], 0x10000
	s_mov_b64 s[14:15], 0x50000
	s_waitcnt vmcnt(0) lgkmcnt(0)
	v_pk_mul_f32 v[210:211], v[126:127], v[192:193] op_sel_hi:[1,0]
	v_pk_mul_f32 v[212:213], v[128:129], v[192:193] op_sel_hi:[1,0]
	v_pk_mul_f32 v[210:211], v[210:211], v[158:159]
	v_pk_mul_f32 v[212:213], v[212:213], v[160:161]
	global_store_dwordx4 v[180:181], v[210:213], off nt
	v_pk_mul_f32 v[214:215], v[122:123], v[192:193] op_sel_hi:[1,0]
	v_pk_mul_f32 v[216:217], v[124:125], v[192:193] op_sel_hi:[1,0]
	v_pk_mul_f32 v[214:215], v[214:215], v[154:155]
	v_pk_mul_f32 v[216:217], v[216:217], v[156:157]
	global_store_dwordx4 v[180:181], v[214:217], off offset:64 nt
	v_pk_mul_f32 v[218:219], v[110:111], v[192:193] op_sel_hi:[1,0]
	v_pk_mul_f32 v[220:221], v[112:113], v[192:193] op_sel_hi:[1,0]
	v_pk_mul_f32 v[218:219], v[218:219], v[150:151]
	v_pk_mul_f32 v[220:221], v[220:221], v[152:153]
	global_store_dwordx4 v[180:181], v[218:221], off offset:512 nt
	v_pk_mul_f32 v[226:227], v[102:103], v[192:193] op_sel_hi:[1,0]
	v_pk_mul_f32 v[228:229], v[104:105], v[192:193] op_sel_hi:[1,0]
	v_pk_mul_f32 v[226:227], v[226:227], v[146:147]
	v_pk_mul_f32 v[228:229], v[228:229], v[148:149]
	global_store_dwordx4 v[180:181], v[226:229], off offset:576 nt
	v_lshl_add_u64 v[180:181], v[180:181], 0, s[24:25]
	v_pk_mul_f32 v[230:231], v[118:119], v[194:195] op_sel_hi:[1,0]
	v_pk_mul_f32 v[232:233], v[120:121], v[194:195] op_sel_hi:[1,0]
	v_pk_mul_f32 v[230:231], v[230:231], v[158:159]
	v_pk_mul_f32 v[232:233], v[232:233], v[160:161]
	global_store_dwordx4 v[180:181], v[230:233], off nt
	v_pk_mul_f32 v[238:239], v[114:115], v[194:195] op_sel_hi:[1,0]
	v_pk_mul_f32 v[240:241], v[116:117], v[194:195] op_sel_hi:[1,0]
	v_pk_mul_f32 v[238:239], v[238:239], v[154:155]
	v_pk_mul_f32 v[240:241], v[240:241], v[156:157]
	global_store_dwordx4 v[180:181], v[238:241], off offset:64 nt
	v_pk_mul_f32 v[242:243], v[94:95], v[194:195] op_sel_hi:[1,0]
	v_pk_mul_f32 v[244:245], v[96:97], v[194:195] op_sel_hi:[1,0]
	v_pk_mul_f32 v[242:243], v[242:243], v[150:151]
	v_pk_mul_f32 v[244:245], v[244:245], v[152:153]
	global_store_dwordx4 v[180:181], v[242:245], off offset:512 nt
	v_pk_mul_f32 v[246:247], v[86:87], v[194:195] op_sel_hi:[1,0]
	v_pk_mul_f32 v[248:249], v[88:89], v[194:195] op_sel_hi:[1,0]
	v_pk_mul_f32 v[246:247], v[246:247], v[146:147]
	v_pk_mul_f32 v[248:249], v[248:249], v[148:149]
	global_store_dwordx4 v[180:181], v[246:249], off offset:576 nt
	v_lshl_add_u64 v[180:181], v[180:181], 0, s[24:25]
	v_pk_mul_f32 v[210:211], v[106:107], v[196:197] op_sel_hi:[1,0]
	v_pk_mul_f32 v[212:213], v[108:109], v[196:197] op_sel_hi:[1,0]
	v_pk_mul_f32 v[210:211], v[210:211], v[158:159]
	v_pk_mul_f32 v[212:213], v[212:213], v[160:161]
	global_store_dwordx4 v[180:181], v[210:213], off nt
	v_pk_mul_f32 v[214:215], v[98:99], v[196:197] op_sel_hi:[1,0]
	v_pk_mul_f32 v[216:217], v[100:101], v[196:197] op_sel_hi:[1,0]
	v_pk_mul_f32 v[214:215], v[214:215], v[154:155]
	v_pk_mul_f32 v[216:217], v[216:217], v[156:157]
	global_store_dwordx4 v[180:181], v[214:217], off offset:64 nt
	v_pk_mul_f32 v[218:219], v[78:79], v[196:197] op_sel_hi:[1,0]
	v_pk_mul_f32 v[220:221], v[80:81], v[196:197] op_sel_hi:[1,0]
	v_pk_mul_f32 v[218:219], v[218:219], v[150:151]
	v_pk_mul_f32 v[220:221], v[220:221], v[152:153]
	global_store_dwordx4 v[180:181], v[218:221], off offset:512 nt
	v_pk_mul_f32 v[226:227], v[74:75], v[196:197] op_sel_hi:[1,0]
	v_pk_mul_f32 v[228:229], v[76:77], v[196:197] op_sel_hi:[1,0]
	v_pk_mul_f32 v[226:227], v[226:227], v[146:147]
	v_pk_mul_f32 v[228:229], v[228:229], v[148:149]
	global_store_dwordx4 v[180:181], v[226:229], off offset:576 nt
	v_lshl_add_u64 v[180:181], v[180:181], 0, s[24:25]
	v_pk_mul_f32 v[230:231], v[90:91], v[198:199] op_sel_hi:[1,0]
	v_pk_mul_f32 v[232:233], v[92:93], v[198:199] op_sel_hi:[1,0]
	v_pk_mul_f32 v[230:231], v[230:231], v[158:159]
	v_pk_mul_f32 v[232:233], v[232:233], v[160:161]
	global_store_dwordx4 v[180:181], v[230:233], off nt
	v_pk_mul_f32 v[238:239], v[82:83], v[198:199] op_sel_hi:[1,0]
	v_pk_mul_f32 v[240:241], v[84:85], v[198:199] op_sel_hi:[1,0]
	v_pk_mul_f32 v[238:239], v[238:239], v[154:155]
	v_pk_mul_f32 v[240:241], v[240:241], v[156:157]
	global_store_dwordx4 v[180:181], v[238:241], off offset:64 nt
	v_pk_mul_f32 v[242:243], v[70:71], v[198:199] op_sel_hi:[1,0]
; #define EN_LOAD(BUF, G) do { const size_t bi_ = (size_t)(row0b + ((G) >> 2) * HALF + ((G) & 3) * 16) * DM + col0b; \
;             _Pragma("unroll") for (int bj = 0; bj < 2; ++bj) _Pragma("unroll") for (int n = 0; n < 2; ++n) BUF[bj][n] = ldb(baseP, bi_ + bj * HALF + n * 16); } while (0)
;     __device__ __forceinline__ void operator()(const f32x4 (&acc)[2][2][4][2], const Unit& u, int wr, int wc, int fr, int fq) const {
;     ...
;         f32x4 bA[2][2], bB[2][2];
;         EN_LOAD(bA, 0); EN_LOAD(bB, 1);
;         EN_DONE(bA, 0); EN_LOAD(bA, 2); EN_DONE(bB, 1); EN_LOAD(bB, 3);
;         EN_DONE(bA, 2); EN_LOAD(bA, 4); EN_DONE(bB, 3); EN_LOAD(bB, 5);
;         EN_DONE(bA, 4); EN_LOAD(bA, 6); EN_DONE(bB, 5); EN_LOAD(bB, 7);
;         EN_DONE(bA, 6); EN_DONE(bB, 7);
	v_pk_mul_f32 v[244:245], v[72:73], v[198:199] op_sel_hi:[1,0]
	v_pk_mul_f32 v[242:243], v[242:243], v[150:151]
	v_pk_mul_f32 v[244:245], v[244:245], v[152:153]
	global_store_dwordx4 v[180:181], v[242:245], off offset:512 nt
	v_pk_mul_f32 v[246:247], v[66:67], v[198:199] op_sel_hi:[1,0]
	v_pk_mul_f32 v[248:249], v[68:69], v[198:199] op_sel_hi:[1,0]
	v_pk_mul_f32 v[246:247], v[246:247], v[146:147]
	v_pk_mul_f32 v[248:249], v[248:249], v[148:149]
	global_store_dwordx4 v[180:181], v[246:249], off offset:576 nt
	v_lshl_add_u64 v[180:181], v[180:181], 0, s[14:15]
	v_pk_mul_f32 v[210:211], v[62:63], v[200:201] op_sel_hi:[1,0]
	v_pk_mul_f32 v[212:213], v[64:65], v[200:201] op_sel_hi:[1,0]
	v_pk_mul_f32 v[210:211], v[210:211], v[158:159]
	v_pk_mul_f32 v[212:213], v[212:213], v[160:161]
	global_store_dwordx4 v[180:181], v[210:213], off nt
	v_pk_mul_f32 v[214:215], v[58:59], v[200:201] op_sel_hi:[1,0]
	v_pk_mul_f32 v[216:217], v[60:61], v[200:201] op_sel_hi:[1,0]
	v_pk_mul_f32 v[214:215], v[214:215], v[154:155]
	v_pk_mul_f32 v[216:217], v[216:217], v[156:157]
	global_store_dwordx4 v[180:181], v[214:217], off offset:64 nt
	v_pk_mul_f32 v[218:219], v[46:47], v[200:201] op_sel_hi:[1,0]
	v_pk_mul_f32 v[220:221], v[48:49], v[200:201] op_sel_hi:[1,0]
	v_pk_mul_f32 v[218:219], v[218:219], v[150:151]
	v_pk_mul_f32 v[220:221], v[220:221], v[152:153]
	global_store_dwordx4 v[180:181], v[218:221], off offset:512 nt
	v_pk_mul_f32 v[226:227], v[38:39], v[200:201] op_sel_hi:[1,0]
	v_pk_mul_f32 v[228:229], v[40:41], v[200:201] op_sel_hi:[1,0]
	v_pk_mul_f32 v[226:227], v[226:227], v[146:147]
	v_pk_mul_f32 v[228:229], v[228:229], v[148:149]
	global_store_dwordx4 v[180:181], v[226:229], off offset:576 nt
	v_lshl_add_u64 v[180:181], v[180:181], 0, s[24:25]
	v_pk_mul_f32 v[230:231], v[54:55], v[202:203] op_sel_hi:[1,0]
	v_pk_mul_f32 v[232:233], v[56:57], v[202:203] op_sel_hi:[1,0]
	v_pk_mul_f32 v[230:231], v[230:231], v[158:159]
	v_pk_mul_f32 v[232:233], v[232:233], v[160:161]
	global_store_dwordx4 v[180:181], v[230:233], off nt
	v_pk_mul_f32 v[238:239], v[50:51], v[202:203] op_sel_hi:[1,0]
	v_pk_mul_f32 v[240:241], v[52:53], v[202:203] op_sel_hi:[1,0]
	v_pk_mul_f32 v[238:239], v[238:239], v[154:155]
	v_pk_mul_f32 v[240:241], v[240:241], v[156:157]
	global_store_dwordx4 v[180:181], v[238:241], off offset:64 nt
	v_pk_mul_f32 v[242:243], v[30:31], v[202:203] op_sel_hi:[1,0]
	v_pk_mul_f32 v[244:245], v[32:33], v[202:203] op_sel_hi:[1,0]
	v_pk_mul_f32 v[242:243], v[242:243], v[150:151]
	v_pk_mul_f32 v[244:245], v[244:245], v[152:153]
	global_store_dwordx4 v[180:181], v[242:245], off offset:512 nt
	v_pk_mul_f32 v[246:247], v[22:23], v[202:203] op_sel_hi:[1,0]
	v_pk_mul_f32 v[248:249], v[24:25], v[202:203] op_sel_hi:[1,0]
	v_pk_mul_f32 v[246:247], v[246:247], v[146:147]
	v_pk_mul_f32 v[248:249], v[248:249], v[148:149]
	global_store_dwordx4 v[180:181], v[246:249], off offset:576 nt
	v_lshl_add_u64 v[180:181], v[180:181], 0, s[24:25]
	v_pk_mul_f32 v[210:211], v[42:43], v[204:205] op_sel_hi:[1,0]
	v_pk_mul_f32 v[212:213], v[44:45], v[204:205] op_sel_hi:[1,0]
	v_pk_mul_f32 v[210:211], v[210:211], v[158:159]
	v_pk_mul_f32 v[212:213], v[212:213], v[160:161]
	global_store_dwordx4 v[180:181], v[210:213], off nt
	v_pk_mul_f32 v[214:215], v[34:35], v[204:205] op_sel_hi:[1,0]
	v_pk_mul_f32 v[216:217], v[36:37], v[204:205] op_sel_hi:[1,0]
	v_pk_mul_f32 v[214:215], v[214:215], v[154:155]
	v_pk_mul_f32 v[216:217], v[216:217], v[156:157]
	global_store_dwordx4 v[180:181], v[214:217], off offset:64 nt
	v_pk_mul_f32 v[218:219], v[14:15], v[204:205] op_sel_hi:[1,0]
	v_pk_mul_f32 v[220:221], v[16:17], v[204:205] op_sel_hi:[1,0]
	v_pk_mul_f32 v[218:219], v[218:219], v[150:151]
	v_pk_mul_f32 v[220:221], v[220:221], v[152:153]
	global_store_dwordx4 v[180:181], v[218:221], off offset:512 nt
	v_pk_mul_f32 v[226:227], v[10:11], v[204:205] op_sel_hi:[1,0]
	v_pk_mul_f32 v[228:229], v[12:13], v[204:205] op_sel_hi:[1,0]
	v_pk_mul_f32 v[226:227], v[226:227], v[146:147]
	v_pk_mul_f32 v[228:229], v[228:229], v[148:149]
	global_store_dwordx4 v[180:181], v[226:229], off offset:576 nt
	v_lshl_add_u64 v[180:181], v[180:181], 0, s[24:25]
	v_pk_mul_f32 v[230:231], v[26:27], v[206:207] op_sel_hi:[1,0]
	v_pk_mul_f32 v[232:233], v[28:29], v[206:207] op_sel_hi:[1,0]
	v_pk_mul_f32 v[230:231], v[230:231], v[158:159]
	v_pk_mul_f32 v[232:233], v[232:233], v[160:161]
	global_store_dwordx4 v[180:181], v[230:233], off nt
	v_pk_mul_f32 v[238:239], v[18:19], v[206:207] op_sel_hi:[1,0]
	v_pk_mul_f32 v[240:241], v[20:21], v[206:207] op_sel_hi:[1,0]
	v_pk_mul_f32 v[238:239], v[238:239], v[154:155]
	v_pk_mul_f32 v[240:241], v[240:241], v[156:157]
	global_store_dwordx4 v[180:181], v[238:241], off offset:64 nt
	v_pk_mul_f32 v[242:243], v[6:7], v[206:207] op_sel_hi:[1,0]
	v_pk_mul_f32 v[244:245], v[8:9], v[206:207] op_sel_hi:[1,0]
	v_pk_mul_f32 v[242:243], v[242:243], v[150:151]
	v_pk_mul_f32 v[244:245], v[244:245], v[152:153]
	global_store_dwordx4 v[180:181], v[242:245], off offset:512 nt
	v_pk_mul_f32 v[246:247], v[2:3], v[206:207] op_sel_hi:[1,0]
	v_pk_mul_f32 v[248:249], v[4:5], v[206:207] op_sel_hi:[1,0]
	v_pk_mul_f32 v[246:247], v[246:247], v[146:147]
	v_pk_mul_f32 v[248:249], v[248:249], v[148:149]
	global_store_dwordx4 v[180:181], v[246:249], off offset:576 nt
	s_mov_b64 s[12:13], 0
